# stagger blocks>=256 by ~18us in phases 1,6,13
# baseline (speedup 1.0000x reference)
.LBB0_101:
	s_cmpk_lt_u32 s82, 0x100
	s_cbranch_scc1 .Lstag_1
	s_movk_i32 s100, 5
